# in-proj rope epilogue re-emitted: 8 lane exchanges per row group in flight together, next group's cos/sin rows + row scale prefetched (on top of merge-epilogue load batching)
# baseline (speedup 1.0000x reference)
.LBB0_419:
	s_andn2_b64 vcc, exec, s[60:61]
	s_cbranch_vccnz .LBB0_421
	v_and_b32_e32 v132, 64, v198
	v_xor_b32_e32 v0, 16, v198
	v_add_u32_e32 v132, 64, v132
	v_cmp_lt_i32_e32 vcc, v0, v132
	s_lshl_b32 s26, s71, 5
	s_mov_b32 s59, s27
	s_mov_b32 s19, s27
	s_mov_b32 s17, s27
	s_mov_b32 s15, s27
	v_cndmask_b32_e32 v0, v198, v0, vcc
	v_lshlrev_b32_e32 v0, 2, v0
	ds_read_b32 v188, v154
	v_lshlrev_b32_e32 v159, 5, v2
	v_and_b32_e32 v159, 0xf9e0, v159
	global_load_dwordx4 v[164:167], v159, s[20:21] offset:16
	global_load_dwordx4 v[160:163], v159, s[20:21]
	global_load_dwordx4 v[172:175], v159, s[22:23] offset:16
	global_load_dwordx4 v[168:171], v159, s[22:23]
	s_waitcnt lgkmcnt(0)
	v_mul_f32_e32 v188, s9, v188
	v_mul_f32_e32 v212, v120, v188
	v_mul_f32_e32 v213, v121, v188
	v_mul_f32_e32 v214, v122, v188
	v_mul_f32_e32 v215, v123, v188
	v_mul_f32_e32 v216, v112, v188
	v_mul_f32_e32 v217, v113, v188
	v_mul_f32_e32 v218, v114, v188
	v_mul_f32_e32 v219, v115, v188
	ds_bpermute_b32 v228, v0, v212
	ds_bpermute_b32 v229, v0, v213
	ds_bpermute_b32 v230, v0, v214
	ds_bpermute_b32 v231, v0, v215
	ds_bpermute_b32 v132, v0, v216
	ds_bpermute_b32 v133, v0, v217
	ds_bpermute_b32 v134, v0, v218
	ds_bpermute_b32 v135, v0, v219
	ds_read_b32 v189, v154 offset:64
	v_or_b32_e32 v143, 0x200, v159
	global_load_dwordx4 v[180:183], v143, s[20:21] offset:16
	global_load_dwordx4 v[176:179], v143, s[20:21]
	global_load_dwordx4 v[190:193], v143, s[22:23] offset:16
	global_load_dwordx4 v[184:187], v143, s[22:23]
	s_waitcnt lgkmcnt(1)
	s_waitcnt vmcnt(4)
	v_cndmask_b32_e64 v228, v228, -v228, s[56:57]
	v_cndmask_b32_e64 v229, v229, -v229, s[56:57]
	v_cndmask_b32_e64 v230, v230, -v230, s[56:57]
	v_cndmask_b32_e64 v231, v231, -v231, s[56:57]
	v_cndmask_b32_e64 v132, v132, -v132, s[56:57]
	v_cndmask_b32_e64 v133, v133, -v133, s[56:57]
	v_cndmask_b32_e64 v134, v134, -v134, s[56:57]
	v_cndmask_b32_e64 v135, v135, -v135, s[56:57]
	v_mul_f32_e32 v160, v212, v160
	v_mul_f32_e32 v161, v213, v161
	v_mul_f32_e32 v162, v214, v162
	v_mul_f32_e32 v163, v215, v163
	v_mul_f32_e32 v164, v216, v164
	v_mul_f32_e32 v165, v217, v165
	v_mul_f32_e32 v166, v218, v166
	v_mul_f32_e32 v167, v219, v167
	v_mul_f32_e32 v168, v228, v168
	v_mul_f32_e32 v169, v229, v169
	v_mul_f32_e32 v170, v230, v170
	v_mul_f32_e32 v171, v231, v171
	v_mul_f32_e32 v172, v132, v172
	v_mul_f32_e32 v173, v133, v173
	v_mul_f32_e32 v174, v134, v174
	v_mul_f32_e32 v175, v135, v175
	v_add_f32_e32 v160, v160, v168
	v_add_f32_e32 v161, v161, v169
	v_add_f32_e32 v162, v162, v170
	v_add_f32_e32 v163, v163, v171
	v_add_f32_e32 v164, v164, v172
	v_add_f32_e32 v165, v165, v173
	v_add_f32_e32 v166, v166, v174
	v_add_f32_e32 v167, v167, v175
	v_cndmask_b32_e64 v212, v212, v160, s[54:55]
	v_cndmask_b32_e64 v213, v213, v161, s[54:55]
	v_cndmask_b32_e64 v214, v214, v162, s[54:55]
	v_cndmask_b32_e64 v215, v215, v163, s[54:55]
	v_cndmask_b32_e64 v216, v216, v164, s[54:55]
	v_cndmask_b32_e64 v217, v217, v165, s[54:55]
	v_cndmask_b32_e64 v218, v218, v166, s[54:55]
	v_cndmask_b32_e64 v219, v219, v167, s[54:55]
	v_cvt_pk_bf16_f32 v228, v212, v213
	v_cvt_pk_bf16_f32 v229, v214, v215
	v_cvt_pk_bf16_f32 v230, v216, v217
	v_cvt_pk_bf16_f32 v231, v218, v219
	global_store_dwordx4 v[140:141], v[228:231], off
	s_waitcnt lgkmcnt(0)
	v_mul_f32_e32 v189, s9, v189
	v_mul_f32_e32 v212, v100, v189
	v_mul_f32_e32 v213, v101, v189
	v_mul_f32_e32 v214, v102, v189
	v_mul_f32_e32 v215, v103, v189
	v_mul_f32_e32 v216, v88, v189
	v_mul_f32_e32 v217, v89, v189
	v_mul_f32_e32 v218, v90, v189
	v_mul_f32_e32 v219, v91, v189
	ds_bpermute_b32 v228, v0, v212
	ds_bpermute_b32 v229, v0, v213
	ds_bpermute_b32 v230, v0, v214
	ds_bpermute_b32 v231, v0, v215
	ds_bpermute_b32 v132, v0, v216
	ds_bpermute_b32 v133, v0, v217
	ds_bpermute_b32 v134, v0, v218
	ds_bpermute_b32 v135, v0, v219
	ds_read_b32 v188, v154 offset:128
	v_or_b32_e32 v143, 0x400, v159
	global_load_dwordx4 v[164:167], v143, s[20:21] offset:16
	global_load_dwordx4 v[160:163], v143, s[20:21]
	global_load_dwordx4 v[172:175], v143, s[22:23] offset:16
	global_load_dwordx4 v[168:171], v143, s[22:23]
	s_waitcnt lgkmcnt(1)
	s_waitcnt vmcnt(5)
	v_cndmask_b32_e64 v228, v228, -v228, s[56:57]
	v_cndmask_b32_e64 v229, v229, -v229, s[56:57]
	v_cndmask_b32_e64 v230, v230, -v230, s[56:57]
	v_cndmask_b32_e64 v231, v231, -v231, s[56:57]
	v_cndmask_b32_e64 v132, v132, -v132, s[56:57]
	v_cndmask_b32_e64 v133, v133, -v133, s[56:57]
	v_cndmask_b32_e64 v134, v134, -v134, s[56:57]
	v_cndmask_b32_e64 v135, v135, -v135, s[56:57]
	v_mul_f32_e32 v176, v212, v176
	v_mul_f32_e32 v177, v213, v177
	v_mul_f32_e32 v178, v214, v178
	v_mul_f32_e32 v179, v215, v179
	v_mul_f32_e32 v180, v216, v180
	v_mul_f32_e32 v181, v217, v181
	v_mul_f32_e32 v182, v218, v182
	v_mul_f32_e32 v183, v219, v183
	v_mul_f32_e32 v184, v228, v184
	v_mul_f32_e32 v185, v229, v185
	v_mul_f32_e32 v186, v230, v186
	v_mul_f32_e32 v187, v231, v187
	v_mul_f32_e32 v190, v132, v190
	v_mul_f32_e32 v191, v133, v191
	v_mul_f32_e32 v192, v134, v192
	v_mul_f32_e32 v193, v135, v193
	v_add_f32_e32 v176, v176, v184
	v_add_f32_e32 v177, v177, v185
	v_add_f32_e32 v178, v178, v186
	v_add_f32_e32 v179, v179, v187
	v_add_f32_e32 v180, v180, v190
	v_add_f32_e32 v181, v181, v191
	v_add_f32_e32 v182, v182, v192
	v_add_f32_e32 v183, v183, v193
	v_cndmask_b32_e64 v212, v212, v176, s[54:55]
	v_cndmask_b32_e64 v213, v213, v177, s[54:55]
	v_cndmask_b32_e64 v214, v214, v178, s[54:55]
	v_cndmask_b32_e64 v215, v215, v179, s[54:55]
	v_cndmask_b32_e64 v216, v216, v180, s[54:55]
	v_cndmask_b32_e64 v217, v217, v181, s[54:55]
	v_cndmask_b32_e64 v218, v218, v182, s[54:55]
	v_cndmask_b32_e64 v219, v219, v183, s[54:55]
	v_cvt_pk_bf16_f32 v228, v212, v213
	v_cvt_pk_bf16_f32 v229, v214, v215
	v_cvt_pk_bf16_f32 v230, v216, v217
	v_cvt_pk_bf16_f32 v231, v218, v219
	v_lshl_add_u64 v[132:133], v[140:141], 0, s[26:27]
	global_store_dwordx4 v[132:133], v[228:231], off
	s_waitcnt lgkmcnt(0)
	v_mul_f32_e32 v188, s9, v188
	v_mul_f32_e32 v212, v68, v188
	v_mul_f32_e32 v213, v69, v188
	v_mul_f32_e32 v214, v70, v188
	v_mul_f32_e32 v215, v71, v188
	v_mul_f32_e32 v216, v56, v188
	v_mul_f32_e32 v217, v57, v188
	v_mul_f32_e32 v218, v58, v188
	v_mul_f32_e32 v219, v59, v188
	ds_bpermute_b32 v228, v0, v212
	ds_bpermute_b32 v229, v0, v213
	ds_bpermute_b32 v230, v0, v214
	ds_bpermute_b32 v231, v0, v215
	ds_bpermute_b32 v132, v0, v216
	ds_bpermute_b32 v133, v0, v217
	ds_bpermute_b32 v134, v0, v218
	ds_bpermute_b32 v135, v0, v219
	ds_read_b32 v189, v154 offset:192
	v_or_b32_e32 v143, 0x600, v159
	global_load_dwordx4 v[180:183], v143, s[20:21] offset:16
	global_load_dwordx4 v[176:179], v143, s[20:21]
	global_load_dwordx4 v[190:193], v143, s[22:23] offset:16
	global_load_dwordx4 v[184:187], v143, s[22:23]
	s_waitcnt lgkmcnt(1)
	s_waitcnt vmcnt(5)
	v_cndmask_b32_e64 v228, v228, -v228, s[56:57]
	v_cndmask_b32_e64 v229, v229, -v229, s[56:57]
	v_cndmask_b32_e64 v230, v230, -v230, s[56:57]
	v_cndmask_b32_e64 v231, v231, -v231, s[56:57]
	v_cndmask_b32_e64 v132, v132, -v132, s[56:57]
	v_cndmask_b32_e64 v133, v133, -v133, s[56:57]
	v_cndmask_b32_e64 v134, v134, -v134, s[56:57]
	v_cndmask_b32_e64 v135, v135, -v135, s[56:57]
	v_mul_f32_e32 v160, v212, v160
	v_mul_f32_e32 v161, v213, v161
	v_mul_f32_e32 v162, v214, v162
	v_mul_f32_e32 v163, v215, v163
	v_mul_f32_e32 v164, v216, v164
	v_mul_f32_e32 v165, v217, v165
	v_mul_f32_e32 v166, v218, v166
	v_mul_f32_e32 v167, v219, v167
	v_mul_f32_e32 v168, v228, v168
	v_mul_f32_e32 v169, v229, v169
	v_mul_f32_e32 v170, v230, v170
	v_mul_f32_e32 v171, v231, v171
	v_mul_f32_e32 v172, v132, v172
	v_mul_f32_e32 v173, v133, v173
	v_mul_f32_e32 v174, v134, v174
	v_mul_f32_e32 v175, v135, v175
	v_add_f32_e32 v160, v160, v168
	v_add_f32_e32 v161, v161, v169
	v_add_f32_e32 v162, v162, v170
	v_add_f32_e32 v163, v163, v171
	v_add_f32_e32 v164, v164, v172
	v_add_f32_e32 v165, v165, v173
	v_add_f32_e32 v166, v166, v174
	v_add_f32_e32 v167, v167, v175
	v_cndmask_b32_e64 v212, v212, v160, s[54:55]
	v_cndmask_b32_e64 v213, v213, v161, s[54:55]
	v_cndmask_b32_e64 v214, v214, v162, s[54:55]
	v_cndmask_b32_e64 v215, v215, v163, s[54:55]
	v_cndmask_b32_e64 v216, v216, v164, s[54:55]
	v_cndmask_b32_e64 v217, v217, v165, s[54:55]
	v_cndmask_b32_e64 v218, v218, v166, s[54:55]
	v_cndmask_b32_e64 v219, v219, v167, s[54:55]
	v_cvt_pk_bf16_f32 v228, v212, v213
	v_cvt_pk_bf16_f32 v229, v214, v215
	v_cvt_pk_bf16_f32 v230, v216, v217
	v_cvt_pk_bf16_f32 v231, v218, v219
	v_lshl_add_u64 v[132:133], s[26:27], 1, v[140:141]
	global_store_dwordx4 v[132:133], v[228:231], off
	s_lshl_b32 s26, s71, 8
	s_waitcnt lgkmcnt(0)
	v_mul_f32_e32 v189, s9, v189
	v_mul_f32_e32 v212, v36, v189
	v_mul_f32_e32 v213, v37, v189
	v_mul_f32_e32 v214, v38, v189
	v_mul_f32_e32 v215, v39, v189
	v_mul_f32_e32 v216, v28, v189
	v_mul_f32_e32 v217, v29, v189
	v_mul_f32_e32 v218, v30, v189
	v_mul_f32_e32 v219, v31, v189
	ds_bpermute_b32 v228, v0, v212
	ds_bpermute_b32 v229, v0, v213
	ds_bpermute_b32 v230, v0, v214
	ds_bpermute_b32 v231, v0, v215
	ds_bpermute_b32 v132, v0, v216
	ds_bpermute_b32 v133, v0, v217
	ds_bpermute_b32 v134, v0, v218
	ds_bpermute_b32 v135, v0, v219
	ds_read_b32 v188, v154 offset:512
	v_mov_b32_e32 v159, 0x400
	v_lshl_add_u32 v159, v2, 3, v159
	v_and_b32_e32 v159, 0x3e78, v159
	v_lshlrev_b32_e32 v159, 2, v159
	global_load_dwordx4 v[164:167], v159, s[20:21] offset:16
	global_load_dwordx4 v[160:163], v159, s[20:21]
	global_load_dwordx4 v[172:175], v159, s[22:23] offset:16
	global_load_dwordx4 v[168:171], v159, s[22:23]
	s_waitcnt lgkmcnt(1)
	s_waitcnt vmcnt(5)
	v_cndmask_b32_e64 v228, v228, -v228, s[56:57]
	v_cndmask_b32_e64 v229, v229, -v229, s[56:57]
	v_cndmask_b32_e64 v230, v230, -v230, s[56:57]
	v_cndmask_b32_e64 v231, v231, -v231, s[56:57]
	v_cndmask_b32_e64 v132, v132, -v132, s[56:57]
	v_cndmask_b32_e64 v133, v133, -v133, s[56:57]
	v_cndmask_b32_e64 v134, v134, -v134, s[56:57]
	v_cndmask_b32_e64 v135, v135, -v135, s[56:57]
	v_mul_f32_e32 v176, v212, v176
	v_mul_f32_e32 v177, v213, v177
	v_mul_f32_e32 v178, v214, v178
	v_mul_f32_e32 v179, v215, v179
	v_mul_f32_e32 v180, v216, v180
	v_mul_f32_e32 v181, v217, v181
	v_mul_f32_e32 v182, v218, v182
	v_mul_f32_e32 v183, v219, v183
	v_mul_f32_e32 v184, v228, v184
	v_mul_f32_e32 v185, v229, v185
	v_mul_f32_e32 v186, v230, v186
	v_mul_f32_e32 v187, v231, v187
	v_mul_f32_e32 v190, v132, v190
	v_mul_f32_e32 v191, v133, v191
	v_mul_f32_e32 v192, v134, v192
	v_mul_f32_e32 v193, v135, v193
	v_add_f32_e32 v176, v176, v184
	v_add_f32_e32 v177, v177, v185
	v_add_f32_e32 v178, v178, v186
	v_add_f32_e32 v179, v179, v187
	v_add_f32_e32 v180, v180, v190
	v_add_f32_e32 v181, v181, v191
	v_add_f32_e32 v182, v182, v192
	v_add_f32_e32 v183, v183, v193
	v_cndmask_b32_e64 v212, v212, v176, s[54:55]
	v_cndmask_b32_e64 v213, v213, v177, s[54:55]
	v_cndmask_b32_e64 v214, v214, v178, s[54:55]
	v_cndmask_b32_e64 v215, v215, v179, s[54:55]
	v_cndmask_b32_e64 v216, v216, v180, s[54:55]
	v_cndmask_b32_e64 v217, v217, v181, s[54:55]
	v_cndmask_b32_e64 v218, v218, v182, s[54:55]
	v_cndmask_b32_e64 v219, v219, v183, s[54:55]
	v_cvt_pk_bf16_f32 v228, v212, v213
	v_cvt_pk_bf16_f32 v229, v214, v215
	v_cvt_pk_bf16_f32 v230, v216, v217
	v_cvt_pk_bf16_f32 v231, v218, v219
	v_lshl_add_u64 v[132:133], s[58:59], 1, v[140:141]
	global_store_dwordx4 v[132:133], v[228:231], off
	s_waitcnt lgkmcnt(0)
	v_mul_f32_e32 v188, s9, v188
	v_mul_f32_e32 v212, v72, v188
	v_mul_f32_e32 v213, v73, v188
	v_mul_f32_e32 v214, v74, v188
	v_mul_f32_e32 v215, v75, v188
	v_mul_f32_e32 v216, v60, v188
	v_mul_f32_e32 v217, v61, v188
	v_mul_f32_e32 v218, v62, v188
	v_mul_f32_e32 v219, v63, v188
	ds_bpermute_b32 v228, v0, v212
	ds_bpermute_b32 v229, v0, v213
	ds_bpermute_b32 v230, v0, v214
	ds_bpermute_b32 v231, v0, v215
	ds_bpermute_b32 v132, v0, v216
	ds_bpermute_b32 v133, v0, v217
	ds_bpermute_b32 v134, v0, v218
	ds_bpermute_b32 v135, v0, v219
	ds_read_b32 v189, v154 offset:576
	v_or_b32_e32 v143, 0x200, v159
	global_load_dwordx4 v[180:183], v143, s[20:21] offset:16
	global_load_dwordx4 v[176:179], v143, s[20:21]
	global_load_dwordx4 v[190:193], v143, s[22:23] offset:16
	global_load_dwordx4 v[184:187], v143, s[22:23]
	s_waitcnt lgkmcnt(1)
	s_waitcnt vmcnt(5)
	v_cndmask_b32_e64 v228, v228, -v228, s[56:57]
	v_cndmask_b32_e64 v229, v229, -v229, s[56:57]
	v_cndmask_b32_e64 v230, v230, -v230, s[56:57]
	v_cndmask_b32_e64 v231, v231, -v231, s[56:57]
	v_cndmask_b32_e64 v132, v132, -v132, s[56:57]
	v_cndmask_b32_e64 v133, v133, -v133, s[56:57]
	v_cndmask_b32_e64 v134, v134, -v134, s[56:57]
	v_cndmask_b32_e64 v135, v135, -v135, s[56:57]
	v_mul_f32_e32 v160, v212, v160
	v_mul_f32_e32 v161, v213, v161
	v_mul_f32_e32 v162, v214, v162
	v_mul_f32_e32 v163, v215, v163
	v_mul_f32_e32 v164, v216, v164
	v_mul_f32_e32 v165, v217, v165
	v_mul_f32_e32 v166, v218, v166
	v_mul_f32_e32 v167, v219, v167
	v_mul_f32_e32 v168, v228, v168
	v_mul_f32_e32 v169, v229, v169
	v_mul_f32_e32 v170, v230, v170
	v_mul_f32_e32 v171, v231, v171
	v_mul_f32_e32 v172, v132, v172
	v_mul_f32_e32 v173, v133, v173
	v_mul_f32_e32 v174, v134, v174
	v_mul_f32_e32 v175, v135, v175
	v_add_f32_e32 v160, v160, v168
	v_add_f32_e32 v161, v161, v169
	v_add_f32_e32 v162, v162, v170
	v_add_f32_e32 v163, v163, v171
	v_add_f32_e32 v164, v164, v172
	v_add_f32_e32 v165, v165, v173
	v_add_f32_e32 v166, v166, v174
	v_add_f32_e32 v167, v167, v175
	v_cndmask_b32_e64 v212, v212, v160, s[54:55]
	v_cndmask_b32_e64 v213, v213, v161, s[54:55]
	v_cndmask_b32_e64 v214, v214, v162, s[54:55]
	v_cndmask_b32_e64 v215, v215, v163, s[54:55]
	v_cndmask_b32_e64 v216, v216, v164, s[54:55]
	v_cndmask_b32_e64 v217, v217, v165, s[54:55]
	v_cndmask_b32_e64 v218, v218, v166, s[54:55]
	v_cndmask_b32_e64 v219, v219, v167, s[54:55]
	v_cvt_pk_bf16_f32 v228, v212, v213
	v_cvt_pk_bf16_f32 v229, v214, v215
	v_cvt_pk_bf16_f32 v230, v216, v217
	v_cvt_pk_bf16_f32 v231, v218, v219
	v_lshl_add_u64 v[132:133], v[140:141], 0, s[26:27]
	global_store_dwordx4 v[132:133], v[228:231], off
	s_waitcnt lgkmcnt(0)
	v_mul_f32_e32 v189, s9, v189
	v_mul_f32_e32 v212, v40, v189
	v_mul_f32_e32 v213, v41, v189
	v_mul_f32_e32 v214, v42, v189
	v_mul_f32_e32 v215, v43, v189
	v_mul_f32_e32 v216, v32, v189
	v_mul_f32_e32 v217, v33, v189
	v_mul_f32_e32 v218, v34, v189
	v_mul_f32_e32 v219, v35, v189
	ds_bpermute_b32 v228, v0, v212
	ds_bpermute_b32 v229, v0, v213
	ds_bpermute_b32 v230, v0, v214
	ds_bpermute_b32 v231, v0, v215
	ds_bpermute_b32 v132, v0, v216
	ds_bpermute_b32 v133, v0, v217
	ds_bpermute_b32 v134, v0, v218
	ds_bpermute_b32 v135, v0, v219
	ds_read_b32 v188, v154 offset:640
	v_or_b32_e32 v143, 0x400, v159
	global_load_dwordx4 v[164:167], v143, s[20:21] offset:16
	global_load_dwordx4 v[160:163], v143, s[20:21]
	global_load_dwordx4 v[172:175], v143, s[22:23] offset:16
	global_load_dwordx4 v[168:171], v143, s[22:23]
	s_waitcnt lgkmcnt(1)
	s_waitcnt vmcnt(5)
	v_cndmask_b32_e64 v228, v228, -v228, s[56:57]
	v_cndmask_b32_e64 v229, v229, -v229, s[56:57]
	v_cndmask_b32_e64 v230, v230, -v230, s[56:57]
	v_cndmask_b32_e64 v231, v231, -v231, s[56:57]
	v_cndmask_b32_e64 v132, v132, -v132, s[56:57]
	v_cndmask_b32_e64 v133, v133, -v133, s[56:57]
	v_cndmask_b32_e64 v134, v134, -v134, s[56:57]
	v_cndmask_b32_e64 v135, v135, -v135, s[56:57]
	v_mul_f32_e32 v176, v212, v176
	v_mul_f32_e32 v177, v213, v177
	v_mul_f32_e32 v178, v214, v178
	v_mul_f32_e32 v179, v215, v179
	v_mul_f32_e32 v180, v216, v180
	v_mul_f32_e32 v181, v217, v181
	v_mul_f32_e32 v182, v218, v182
	v_mul_f32_e32 v183, v219, v183
	v_mul_f32_e32 v184, v228, v184
	v_mul_f32_e32 v185, v229, v185
	v_mul_f32_e32 v186, v230, v186
	v_mul_f32_e32 v187, v231, v187
	v_mul_f32_e32 v190, v132, v190
	v_mul_f32_e32 v191, v133, v191
	v_mul_f32_e32 v192, v134, v192
	v_mul_f32_e32 v193, v135, v193
	v_add_f32_e32 v176, v176, v184
	v_add_f32_e32 v177, v177, v185
	v_add_f32_e32 v178, v178, v186
	v_add_f32_e32 v179, v179, v187
	v_add_f32_e32 v180, v180, v190
	v_add_f32_e32 v181, v181, v191
	v_add_f32_e32 v182, v182, v192
	v_add_f32_e32 v183, v183, v193
	v_cndmask_b32_e64 v212, v212, v176, s[54:55]
	v_cndmask_b32_e64 v213, v213, v177, s[54:55]
	v_cndmask_b32_e64 v214, v214, v178, s[54:55]
	v_cndmask_b32_e64 v215, v215, v179, s[54:55]
	v_cndmask_b32_e64 v216, v216, v180, s[54:55]
	v_cndmask_b32_e64 v217, v217, v181, s[54:55]
	v_cndmask_b32_e64 v218, v218, v182, s[54:55]
	v_cndmask_b32_e64 v219, v219, v183, s[54:55]
	v_cvt_pk_bf16_f32 v228, v212, v213
	v_cvt_pk_bf16_f32 v229, v214, v215
	v_cvt_pk_bf16_f32 v230, v216, v217
	v_cvt_pk_bf16_f32 v231, v218, v219
	v_lshl_add_u64 v[132:133], s[18:19], 1, v[140:141]
	global_store_dwordx4 v[132:133], v[228:231], off
	s_waitcnt lgkmcnt(0)
	v_mul_f32_e32 v188, s9, v188
	v_mul_f32_e32 v212, v16, v188
	v_mul_f32_e32 v213, v17, v188
	v_mul_f32_e32 v214, v18, v188
	v_mul_f32_e32 v215, v19, v188
	v_mul_f32_e32 v216, v12, v188
	v_mul_f32_e32 v217, v13, v188
	v_mul_f32_e32 v218, v14, v188
	v_mul_f32_e32 v219, v15, v188
	ds_bpermute_b32 v228, v0, v212
	ds_bpermute_b32 v229, v0, v213
	ds_bpermute_b32 v230, v0, v214
	ds_bpermute_b32 v231, v0, v215
	ds_bpermute_b32 v132, v0, v216
	ds_bpermute_b32 v133, v0, v217
	ds_bpermute_b32 v134, v0, v218
	ds_bpermute_b32 v135, v0, v219
	ds_read_b32 v189, v154 offset:704
	v_or_b32_e32 v143, 0x600, v159
	global_load_dwordx4 v[180:183], v143, s[20:21] offset:16
	global_load_dwordx4 v[176:179], v143, s[20:21]
	global_load_dwordx4 v[190:193], v143, s[22:23] offset:16
	global_load_dwordx4 v[184:187], v143, s[22:23]
	s_waitcnt lgkmcnt(1)
	s_waitcnt vmcnt(5)
	v_cndmask_b32_e64 v228, v228, -v228, s[56:57]
	v_cndmask_b32_e64 v229, v229, -v229, s[56:57]
	v_cndmask_b32_e64 v230, v230, -v230, s[56:57]
	v_cndmask_b32_e64 v231, v231, -v231, s[56:57]
	v_cndmask_b32_e64 v132, v132, -v132, s[56:57]
	v_cndmask_b32_e64 v133, v133, -v133, s[56:57]
	v_cndmask_b32_e64 v134, v134, -v134, s[56:57]
	v_cndmask_b32_e64 v135, v135, -v135, s[56:57]
	v_mul_f32_e32 v160, v212, v160
	v_mul_f32_e32 v161, v213, v161
	v_mul_f32_e32 v162, v214, v162
	v_mul_f32_e32 v163, v215, v163
	v_mul_f32_e32 v164, v216, v164
	v_mul_f32_e32 v165, v217, v165
	v_mul_f32_e32 v166, v218, v166
	v_mul_f32_e32 v167, v219, v167
	v_mul_f32_e32 v168, v228, v168
	v_mul_f32_e32 v169, v229, v169
	v_mul_f32_e32 v170, v230, v170
	v_mul_f32_e32 v171, v231, v171
	v_mul_f32_e32 v172, v132, v172
	v_mul_f32_e32 v173, v133, v173
	v_mul_f32_e32 v174, v134, v174
	v_mul_f32_e32 v175, v135, v175
	v_add_f32_e32 v160, v160, v168
	v_add_f32_e32 v161, v161, v169
	v_add_f32_e32 v162, v162, v170
	v_add_f32_e32 v163, v163, v171
	v_add_f32_e32 v164, v164, v172
	v_add_f32_e32 v165, v165, v173
	v_add_f32_e32 v166, v166, v174
	v_add_f32_e32 v167, v167, v175
	v_cndmask_b32_e64 v212, v212, v160, s[54:55]
	v_cndmask_b32_e64 v213, v213, v161, s[54:55]
	v_cndmask_b32_e64 v214, v214, v162, s[54:55]
	v_cndmask_b32_e64 v215, v215, v163, s[54:55]
	v_cndmask_b32_e64 v216, v216, v164, s[54:55]
	v_cndmask_b32_e64 v217, v217, v165, s[54:55]
	v_cndmask_b32_e64 v218, v218, v166, s[54:55]
	v_cndmask_b32_e64 v219, v219, v167, s[54:55]
	v_cvt_pk_bf16_f32 v228, v212, v213
	v_cvt_pk_bf16_f32 v229, v214, v215
	v_cvt_pk_bf16_f32 v230, v216, v217
	v_cvt_pk_bf16_f32 v231, v218, v219
	v_lshl_add_u64 v[132:133], s[16:17], 1, v[140:141]
	global_store_dwordx4 v[132:133], v[228:231], off
	s_waitcnt lgkmcnt(0)
	v_mul_f32_e32 v189, s9, v189
	v_mul_f32_e32 v212, v8, v189
	v_mul_f32_e32 v213, v9, v189
	v_mul_f32_e32 v214, v10, v189
	v_mul_f32_e32 v215, v11, v189
	v_mul_f32_e32 v216, v4, v189
	v_mul_f32_e32 v217, v5, v189
	v_mul_f32_e32 v218, v6, v189
	v_mul_f32_e32 v219, v7, v189
	ds_bpermute_b32 v228, v0, v212
	ds_bpermute_b32 v229, v0, v213
	ds_bpermute_b32 v230, v0, v214
	ds_bpermute_b32 v231, v0, v215
	ds_bpermute_b32 v132, v0, v216
	ds_bpermute_b32 v133, v0, v217
	ds_bpermute_b32 v134, v0, v218
	ds_bpermute_b32 v135, v0, v219
	s_waitcnt lgkmcnt(0)
	s_waitcnt vmcnt(1)
	v_cndmask_b32_e64 v228, v228, -v228, s[56:57]
	v_cndmask_b32_e64 v229, v229, -v229, s[56:57]
	v_cndmask_b32_e64 v230, v230, -v230, s[56:57]
	v_cndmask_b32_e64 v231, v231, -v231, s[56:57]
	v_cndmask_b32_e64 v132, v132, -v132, s[56:57]
	v_cndmask_b32_e64 v133, v133, -v133, s[56:57]
	v_cndmask_b32_e64 v134, v134, -v134, s[56:57]
	v_cndmask_b32_e64 v135, v135, -v135, s[56:57]
	v_mul_f32_e32 v176, v212, v176
	v_mul_f32_e32 v177, v213, v177
	v_mul_f32_e32 v178, v214, v178
	v_mul_f32_e32 v179, v215, v179
	v_mul_f32_e32 v180, v216, v180
	v_mul_f32_e32 v181, v217, v181
	v_mul_f32_e32 v182, v218, v182
	v_mul_f32_e32 v183, v219, v183
	v_mul_f32_e32 v184, v228, v184
	v_mul_f32_e32 v185, v229, v185
	v_mul_f32_e32 v186, v230, v186
	v_mul_f32_e32 v187, v231, v187
	v_mul_f32_e32 v190, v132, v190
	v_mul_f32_e32 v191, v133, v191
	v_mul_f32_e32 v192, v134, v192
	v_mul_f32_e32 v193, v135, v193
	v_add_f32_e32 v176, v176, v184
	v_add_f32_e32 v177, v177, v185
	v_add_f32_e32 v178, v178, v186
	v_add_f32_e32 v179, v179, v187
	v_add_f32_e32 v180, v180, v190
	v_add_f32_e32 v181, v181, v191
	v_add_f32_e32 v182, v182, v192
	v_add_f32_e32 v183, v183, v193
	v_cndmask_b32_e64 v212, v212, v176, s[54:55]
	v_cndmask_b32_e64 v213, v213, v177, s[54:55]
	v_cndmask_b32_e64 v214, v214, v178, s[54:55]
	v_cndmask_b32_e64 v215, v215, v179, s[54:55]
	v_cndmask_b32_e64 v216, v216, v180, s[54:55]
	v_cndmask_b32_e64 v217, v217, v181, s[54:55]
	v_cndmask_b32_e64 v218, v218, v182, s[54:55]
	v_cndmask_b32_e64 v219, v219, v183, s[54:55]
	v_cvt_pk_bf16_f32 v228, v212, v213
	v_cvt_pk_bf16_f32 v229, v214, v215
	v_cvt_pk_bf16_f32 v230, v216, v217
	v_cvt_pk_bf16_f32 v231, v218, v219
	v_lshl_add_u64 v[132:133], s[14:15], 1, v[140:141]
	global_store_dwordx4 v[132:133], v[228:231], off

.LBB0_450:
	s_andn2_b64 vcc, exec, s[58:59]
	s_cbranch_vccnz .LBB0_452
	v_and_b32_e32 v132, 64, v198
	v_xor_b32_e32 v0, 16, v198
	v_add_u32_e32 v132, 64, v132
	v_cmp_lt_i32_e32 vcc, v0, v132
	s_lshl_b32 s26, s61, 5
	s_mov_b32 s19, s27
	s_mov_b32 s17, s27
	s_mov_b32 s15, s27
	s_mov_b32 s13, s27
	v_cndmask_b32_e32 v0, v198, v0, vcc
	v_lshlrev_b32_e32 v0, 2, v0
	ds_read_b32 v188, v154
	v_lshlrev_b32_e32 v159, 5, v2
	v_and_b32_e32 v159, 0xf9e0, v159
	global_load_dwordx4 v[164:167], v159, s[20:21] offset:16
	global_load_dwordx4 v[160:163], v159, s[20:21]
	global_load_dwordx4 v[172:175], v159, s[22:23] offset:16
	global_load_dwordx4 v[168:171], v159, s[22:23]
	s_waitcnt lgkmcnt(0)
	v_mul_f32_e32 v188, s9, v188
	v_mul_f32_e32 v212, v128, v188
	v_mul_f32_e32 v213, v129, v188
	v_mul_f32_e32 v214, v130, v188
	v_mul_f32_e32 v215, v131, v188
	v_mul_f32_e32 v216, v124, v188
	v_mul_f32_e32 v217, v125, v188
	v_mul_f32_e32 v218, v126, v188
	v_mul_f32_e32 v219, v127, v188
	ds_bpermute_b32 v228, v0, v212
	ds_bpermute_b32 v229, v0, v213
	ds_bpermute_b32 v230, v0, v214
	ds_bpermute_b32 v231, v0, v215
	ds_bpermute_b32 v132, v0, v216
	ds_bpermute_b32 v133, v0, v217
	ds_bpermute_b32 v134, v0, v218
	ds_bpermute_b32 v135, v0, v219
	ds_read_b32 v189, v154 offset:64
	v_or_b32_e32 v136, 0x200, v159
	global_load_dwordx4 v[180:183], v136, s[20:21] offset:16
	global_load_dwordx4 v[176:179], v136, s[20:21]
	global_load_dwordx4 v[190:193], v136, s[22:23] offset:16
	global_load_dwordx4 v[184:187], v136, s[22:23]
	s_waitcnt lgkmcnt(1)
	s_waitcnt vmcnt(4)
	v_cndmask_b32_e64 v228, v228, -v228, s[56:57]
	v_cndmask_b32_e64 v229, v229, -v229, s[56:57]
	v_cndmask_b32_e64 v230, v230, -v230, s[56:57]
	v_cndmask_b32_e64 v231, v231, -v231, s[56:57]
	v_cndmask_b32_e64 v132, v132, -v132, s[56:57]
	v_cndmask_b32_e64 v133, v133, -v133, s[56:57]
	v_cndmask_b32_e64 v134, v134, -v134, s[56:57]
	v_cndmask_b32_e64 v135, v135, -v135, s[56:57]
	v_mul_f32_e32 v160, v212, v160
	v_mul_f32_e32 v161, v213, v161
	v_mul_f32_e32 v162, v214, v162
	v_mul_f32_e32 v163, v215, v163
	v_mul_f32_e32 v164, v216, v164
	v_mul_f32_e32 v165, v217, v165
	v_mul_f32_e32 v166, v218, v166
	v_mul_f32_e32 v167, v219, v167
	v_mul_f32_e32 v168, v228, v168
	v_mul_f32_e32 v169, v229, v169
	v_mul_f32_e32 v170, v230, v170
	v_mul_f32_e32 v171, v231, v171
	v_mul_f32_e32 v172, v132, v172
	v_mul_f32_e32 v173, v133, v173
	v_mul_f32_e32 v174, v134, v174
	v_mul_f32_e32 v175, v135, v175
	v_add_f32_e32 v160, v160, v168
	v_add_f32_e32 v161, v161, v169
	v_add_f32_e32 v162, v162, v170
	v_add_f32_e32 v163, v163, v171
	v_add_f32_e32 v164, v164, v172
	v_add_f32_e32 v165, v165, v173
	v_add_f32_e32 v166, v166, v174
	v_add_f32_e32 v167, v167, v175
	v_cndmask_b32_e64 v212, v212, v160, s[54:55]
	v_cndmask_b32_e64 v213, v213, v161, s[54:55]
	v_cndmask_b32_e64 v214, v214, v162, s[54:55]
	v_cndmask_b32_e64 v215, v215, v163, s[54:55]
	v_cndmask_b32_e64 v216, v216, v164, s[54:55]
	v_cndmask_b32_e64 v217, v217, v165, s[54:55]
	v_cndmask_b32_e64 v218, v218, v166, s[54:55]
	v_cndmask_b32_e64 v219, v219, v167, s[54:55]
	v_cvt_pk_bf16_f32 v228, v212, v213
	v_cvt_pk_bf16_f32 v229, v214, v215
	v_cvt_pk_bf16_f32 v230, v216, v217
	v_cvt_pk_bf16_f32 v231, v218, v219
	global_store_dwordx4 v[142:143], v[228:231], off
	s_waitcnt lgkmcnt(0)
	v_mul_f32_e32 v189, s9, v189
	v_mul_f32_e32 v212, v116, v189
	v_mul_f32_e32 v213, v117, v189
	v_mul_f32_e32 v214, v118, v189
	v_mul_f32_e32 v215, v119, v189
	v_mul_f32_e32 v216, v108, v189
	v_mul_f32_e32 v217, v109, v189
	v_mul_f32_e32 v218, v110, v189
	v_mul_f32_e32 v219, v111, v189
	ds_bpermute_b32 v228, v0, v212
	ds_bpermute_b32 v229, v0, v213
	ds_bpermute_b32 v230, v0, v214
	ds_bpermute_b32 v231, v0, v215
	ds_bpermute_b32 v132, v0, v216
	ds_bpermute_b32 v133, v0, v217
	ds_bpermute_b32 v134, v0, v218
	ds_bpermute_b32 v135, v0, v219
	ds_read_b32 v188, v154 offset:128
	v_or_b32_e32 v136, 0x400, v159
	global_load_dwordx4 v[164:167], v136, s[20:21] offset:16
	global_load_dwordx4 v[160:163], v136, s[20:21]
	global_load_dwordx4 v[172:175], v136, s[22:23] offset:16
	global_load_dwordx4 v[168:171], v136, s[22:23]
	s_waitcnt lgkmcnt(1)
	s_waitcnt vmcnt(5)
	v_cndmask_b32_e64 v228, v228, -v228, s[56:57]
	v_cndmask_b32_e64 v229, v229, -v229, s[56:57]
	v_cndmask_b32_e64 v230, v230, -v230, s[56:57]
	v_cndmask_b32_e64 v231, v231, -v231, s[56:57]
	v_cndmask_b32_e64 v132, v132, -v132, s[56:57]
	v_cndmask_b32_e64 v133, v133, -v133, s[56:57]
	v_cndmask_b32_e64 v134, v134, -v134, s[56:57]
	v_cndmask_b32_e64 v135, v135, -v135, s[56:57]
	v_mul_f32_e32 v176, v212, v176
	v_mul_f32_e32 v177, v213, v177
	v_mul_f32_e32 v178, v214, v178
	v_mul_f32_e32 v179, v215, v179
	v_mul_f32_e32 v180, v216, v180
	v_mul_f32_e32 v181, v217, v181
	v_mul_f32_e32 v182, v218, v182
	v_mul_f32_e32 v183, v219, v183
	v_mul_f32_e32 v184, v228, v184
	v_mul_f32_e32 v185, v229, v185
	v_mul_f32_e32 v186, v230, v186
	v_mul_f32_e32 v187, v231, v187
	v_mul_f32_e32 v190, v132, v190
	v_mul_f32_e32 v191, v133, v191
	v_mul_f32_e32 v192, v134, v192
	v_mul_f32_e32 v193, v135, v193
	v_add_f32_e32 v176, v176, v184
	v_add_f32_e32 v177, v177, v185
	v_add_f32_e32 v178, v178, v186
	v_add_f32_e32 v179, v179, v187
	v_add_f32_e32 v180, v180, v190
	v_add_f32_e32 v181, v181, v191
	v_add_f32_e32 v182, v182, v192
	v_add_f32_e32 v183, v183, v193
	v_cndmask_b32_e64 v212, v212, v176, s[54:55]
	v_cndmask_b32_e64 v213, v213, v177, s[54:55]
	v_cndmask_b32_e64 v214, v214, v178, s[54:55]
	v_cndmask_b32_e64 v215, v215, v179, s[54:55]
	v_cndmask_b32_e64 v216, v216, v180, s[54:55]
	v_cndmask_b32_e64 v217, v217, v181, s[54:55]
	v_cndmask_b32_e64 v218, v218, v182, s[54:55]
	v_cndmask_b32_e64 v219, v219, v183, s[54:55]
	v_cvt_pk_bf16_f32 v228, v212, v213
	v_cvt_pk_bf16_f32 v229, v214, v215
	v_cvt_pk_bf16_f32 v230, v216, v217
	v_cvt_pk_bf16_f32 v231, v218, v219
	v_lshl_add_u64 v[132:133], v[142:143], 0, s[26:27]
	global_store_dwordx4 v[132:133], v[228:231], off
	s_waitcnt lgkmcnt(0)
	v_mul_f32_e32 v188, s9, v188
	v_mul_f32_e32 v212, v92, v188
	v_mul_f32_e32 v213, v93, v188
	v_mul_f32_e32 v214, v94, v188
	v_mul_f32_e32 v215, v95, v188
	v_mul_f32_e32 v216, v80, v188
	v_mul_f32_e32 v217, v81, v188
	v_mul_f32_e32 v218, v82, v188
	v_mul_f32_e32 v219, v83, v188
	ds_bpermute_b32 v228, v0, v212
	ds_bpermute_b32 v229, v0, v213
	ds_bpermute_b32 v230, v0, v214
	ds_bpermute_b32 v231, v0, v215
	ds_bpermute_b32 v132, v0, v216
	ds_bpermute_b32 v133, v0, v217
	ds_bpermute_b32 v134, v0, v218
	ds_bpermute_b32 v135, v0, v219
	ds_read_b32 v189, v154 offset:192
	v_or_b32_e32 v136, 0x600, v159
	global_load_dwordx4 v[180:183], v136, s[20:21] offset:16
	global_load_dwordx4 v[176:179], v136, s[20:21]
	global_load_dwordx4 v[190:193], v136, s[22:23] offset:16
	global_load_dwordx4 v[184:187], v136, s[22:23]
	s_waitcnt lgkmcnt(1)
	s_waitcnt vmcnt(5)
	v_cndmask_b32_e64 v228, v228, -v228, s[56:57]
	v_cndmask_b32_e64 v229, v229, -v229, s[56:57]
	v_cndmask_b32_e64 v230, v230, -v230, s[56:57]
	v_cndmask_b32_e64 v231, v231, -v231, s[56:57]
	v_cndmask_b32_e64 v132, v132, -v132, s[56:57]
	v_cndmask_b32_e64 v133, v133, -v133, s[56:57]
	v_cndmask_b32_e64 v134, v134, -v134, s[56:57]
	v_cndmask_b32_e64 v135, v135, -v135, s[56:57]
	v_mul_f32_e32 v160, v212, v160
	v_mul_f32_e32 v161, v213, v161
	v_mul_f32_e32 v162, v214, v162
	v_mul_f32_e32 v163, v215, v163
	v_mul_f32_e32 v164, v216, v164
	v_mul_f32_e32 v165, v217, v165
	v_mul_f32_e32 v166, v218, v166
	v_mul_f32_e32 v167, v219, v167
	v_mul_f32_e32 v168, v228, v168
	v_mul_f32_e32 v169, v229, v169
	v_mul_f32_e32 v170, v230, v170
	v_mul_f32_e32 v171, v231, v171
	v_mul_f32_e32 v172, v132, v172
	v_mul_f32_e32 v173, v133, v173
	v_mul_f32_e32 v174, v134, v174
	v_mul_f32_e32 v175, v135, v175
	v_add_f32_e32 v160, v160, v168
	v_add_f32_e32 v161, v161, v169
	v_add_f32_e32 v162, v162, v170
	v_add_f32_e32 v163, v163, v171
	v_add_f32_e32 v164, v164, v172
	v_add_f32_e32 v165, v165, v173
	v_add_f32_e32 v166, v166, v174
	v_add_f32_e32 v167, v167, v175
	v_cndmask_b32_e64 v212, v212, v160, s[54:55]
	v_cndmask_b32_e64 v213, v213, v161, s[54:55]
	v_cndmask_b32_e64 v214, v214, v162, s[54:55]
	v_cndmask_b32_e64 v215, v215, v163, s[54:55]
	v_cndmask_b32_e64 v216, v216, v164, s[54:55]
	v_cndmask_b32_e64 v217, v217, v165, s[54:55]
	v_cndmask_b32_e64 v218, v218, v166, s[54:55]
	v_cndmask_b32_e64 v219, v219, v167, s[54:55]
	v_cvt_pk_bf16_f32 v228, v212, v213
	v_cvt_pk_bf16_f32 v229, v214, v215
	v_cvt_pk_bf16_f32 v230, v216, v217
	v_cvt_pk_bf16_f32 v231, v218, v219
	v_lshl_add_u64 v[132:133], s[26:27], 1, v[142:143]
	global_store_dwordx4 v[132:133], v[228:231], off
	s_lshl_b32 s26, s61, 8
	s_waitcnt lgkmcnt(0)
	v_mul_f32_e32 v189, s9, v189
	v_mul_f32_e32 v212, v64, v189
	v_mul_f32_e32 v213, v65, v189
	v_mul_f32_e32 v214, v66, v189
	v_mul_f32_e32 v215, v67, v189
	v_mul_f32_e32 v216, v48, v189
	v_mul_f32_e32 v217, v49, v189
	v_mul_f32_e32 v218, v50, v189
	v_mul_f32_e32 v219, v51, v189
	ds_bpermute_b32 v228, v0, v212
	ds_bpermute_b32 v229, v0, v213
	ds_bpermute_b32 v230, v0, v214
	ds_bpermute_b32 v231, v0, v215
	ds_bpermute_b32 v132, v0, v216
	ds_bpermute_b32 v133, v0, v217
	ds_bpermute_b32 v134, v0, v218
	ds_bpermute_b32 v135, v0, v219
	ds_read_b32 v188, v154 offset:512
	v_mov_b32_e32 v159, 0x400
	v_lshl_add_u32 v159, v2, 3, v159
	v_and_b32_e32 v159, 0x3e78, v159
	v_lshlrev_b32_e32 v159, 2, v159
	global_load_dwordx4 v[164:167], v159, s[20:21] offset:16
	global_load_dwordx4 v[160:163], v159, s[20:21]
	global_load_dwordx4 v[172:175], v159, s[22:23] offset:16
	global_load_dwordx4 v[168:171], v159, s[22:23]
	s_waitcnt lgkmcnt(1)
	s_waitcnt vmcnt(5)
	v_cndmask_b32_e64 v228, v228, -v228, s[56:57]
	v_cndmask_b32_e64 v229, v229, -v229, s[56:57]
	v_cndmask_b32_e64 v230, v230, -v230, s[56:57]
	v_cndmask_b32_e64 v231, v231, -v231, s[56:57]
	v_cndmask_b32_e64 v132, v132, -v132, s[56:57]
	v_cndmask_b32_e64 v133, v133, -v133, s[56:57]
	v_cndmask_b32_e64 v134, v134, -v134, s[56:57]
	v_cndmask_b32_e64 v135, v135, -v135, s[56:57]
	v_mul_f32_e32 v176, v212, v176
	v_mul_f32_e32 v177, v213, v177
	v_mul_f32_e32 v178, v214, v178
	v_mul_f32_e32 v179, v215, v179
	v_mul_f32_e32 v180, v216, v180
	v_mul_f32_e32 v181, v217, v181
	v_mul_f32_e32 v182, v218, v182
	v_mul_f32_e32 v183, v219, v183
	v_mul_f32_e32 v184, v228, v184
	v_mul_f32_e32 v185, v229, v185
	v_mul_f32_e32 v186, v230, v186
	v_mul_f32_e32 v187, v231, v187
	v_mul_f32_e32 v190, v132, v190
	v_mul_f32_e32 v191, v133, v191
	v_mul_f32_e32 v192, v134, v192
	v_mul_f32_e32 v193, v135, v193
	v_add_f32_e32 v176, v176, v184
	v_add_f32_e32 v177, v177, v185
	v_add_f32_e32 v178, v178, v186
	v_add_f32_e32 v179, v179, v187
	v_add_f32_e32 v180, v180, v190
	v_add_f32_e32 v181, v181, v191
	v_add_f32_e32 v182, v182, v192
	v_add_f32_e32 v183, v183, v193
	v_cndmask_b32_e64 v212, v212, v176, s[54:55]
	v_cndmask_b32_e64 v213, v213, v177, s[54:55]
	v_cndmask_b32_e64 v214, v214, v178, s[54:55]
	v_cndmask_b32_e64 v215, v215, v179, s[54:55]
	v_cndmask_b32_e64 v216, v216, v180, s[54:55]
	v_cndmask_b32_e64 v217, v217, v181, s[54:55]
	v_cndmask_b32_e64 v218, v218, v182, s[54:55]
	v_cndmask_b32_e64 v219, v219, v183, s[54:55]
	v_cvt_pk_bf16_f32 v228, v212, v213
	v_cvt_pk_bf16_f32 v229, v214, v215
	v_cvt_pk_bf16_f32 v230, v216, v217
	v_cvt_pk_bf16_f32 v231, v218, v219
	v_lshl_add_u64 v[132:133], s[18:19], 1, v[142:143]
	global_store_dwordx4 v[132:133], v[228:231], off
	s_waitcnt lgkmcnt(0)
	v_mul_f32_e32 v188, s9, v188
	v_mul_f32_e32 v212, v96, v188
	v_mul_f32_e32 v213, v97, v188
	v_mul_f32_e32 v214, v98, v188
	v_mul_f32_e32 v215, v99, v188
	v_mul_f32_e32 v216, v104, v188
	v_mul_f32_e32 v217, v105, v188
	v_mul_f32_e32 v218, v106, v188
	v_mul_f32_e32 v219, v107, v188
	ds_bpermute_b32 v228, v0, v212
	ds_bpermute_b32 v229, v0, v213
	ds_bpermute_b32 v230, v0, v214
	ds_bpermute_b32 v231, v0, v215
	ds_bpermute_b32 v132, v0, v216
	ds_bpermute_b32 v133, v0, v217
	ds_bpermute_b32 v134, v0, v218
	ds_bpermute_b32 v135, v0, v219
	ds_read_b32 v189, v154 offset:576
	v_or_b32_e32 v136, 0x200, v159
	global_load_dwordx4 v[180:183], v136, s[20:21] offset:16
	global_load_dwordx4 v[176:179], v136, s[20:21]
	global_load_dwordx4 v[190:193], v136, s[22:23] offset:16
	global_load_dwordx4 v[184:187], v136, s[22:23]
	s_waitcnt lgkmcnt(1)
	s_waitcnt vmcnt(5)
	v_cndmask_b32_e64 v228, v228, -v228, s[56:57]
	v_cndmask_b32_e64 v229, v229, -v229, s[56:57]
	v_cndmask_b32_e64 v230, v230, -v230, s[56:57]
	v_cndmask_b32_e64 v231, v231, -v231, s[56:57]
	v_cndmask_b32_e64 v132, v132, -v132, s[56:57]
	v_cndmask_b32_e64 v133, v133, -v133, s[56:57]
	v_cndmask_b32_e64 v134, v134, -v134, s[56:57]
	v_cndmask_b32_e64 v135, v135, -v135, s[56:57]
	v_mul_f32_e32 v160, v212, v160
	v_mul_f32_e32 v161, v213, v161
	v_mul_f32_e32 v162, v214, v162
	v_mul_f32_e32 v163, v215, v163
	v_mul_f32_e32 v164, v216, v164
	v_mul_f32_e32 v165, v217, v165
	v_mul_f32_e32 v166, v218, v166
	v_mul_f32_e32 v167, v219, v167
	v_mul_f32_e32 v168, v228, v168
	v_mul_f32_e32 v169, v229, v169
	v_mul_f32_e32 v170, v230, v170
	v_mul_f32_e32 v171, v231, v171
	v_mul_f32_e32 v172, v132, v172
	v_mul_f32_e32 v173, v133, v173
	v_mul_f32_e32 v174, v134, v174
	v_mul_f32_e32 v175, v135, v175
	v_add_f32_e32 v160, v160, v168
	v_add_f32_e32 v161, v161, v169
	v_add_f32_e32 v162, v162, v170
	v_add_f32_e32 v163, v163, v171
	v_add_f32_e32 v164, v164, v172
	v_add_f32_e32 v165, v165, v173
	v_add_f32_e32 v166, v166, v174
	v_add_f32_e32 v167, v167, v175
	v_cndmask_b32_e64 v212, v212, v160, s[54:55]
	v_cndmask_b32_e64 v213, v213, v161, s[54:55]
	v_cndmask_b32_e64 v214, v214, v162, s[54:55]
	v_cndmask_b32_e64 v215, v215, v163, s[54:55]
	v_cndmask_b32_e64 v216, v216, v164, s[54:55]
	v_cndmask_b32_e64 v217, v217, v165, s[54:55]
	v_cndmask_b32_e64 v218, v218, v166, s[54:55]
	v_cndmask_b32_e64 v219, v219, v167, s[54:55]
	v_cvt_pk_bf16_f32 v228, v212, v213
	v_cvt_pk_bf16_f32 v229, v214, v215
	v_cvt_pk_bf16_f32 v230, v216, v217
	v_cvt_pk_bf16_f32 v231, v218, v219
	v_lshl_add_u64 v[132:133], v[142:143], 0, s[26:27]
	global_store_dwordx4 v[132:133], v[228:231], off
	s_waitcnt lgkmcnt(0)
	v_mul_f32_e32 v189, s9, v189
	v_mul_f32_e32 v212, v84, v189
	v_mul_f32_e32 v213, v85, v189
	v_mul_f32_e32 v214, v86, v189
	v_mul_f32_e32 v215, v87, v189
	v_mul_f32_e32 v216, v76, v189
	v_mul_f32_e32 v217, v77, v189
	v_mul_f32_e32 v218, v78, v189
	v_mul_f32_e32 v219, v79, v189
	ds_bpermute_b32 v228, v0, v212
	ds_bpermute_b32 v229, v0, v213
	ds_bpermute_b32 v230, v0, v214
	ds_bpermute_b32 v231, v0, v215
	ds_bpermute_b32 v132, v0, v216
	ds_bpermute_b32 v133, v0, v217
	ds_bpermute_b32 v134, v0, v218
	ds_bpermute_b32 v135, v0, v219
	ds_read_b32 v188, v154 offset:640
	v_or_b32_e32 v136, 0x400, v159
	global_load_dwordx4 v[164:167], v136, s[20:21] offset:16
	global_load_dwordx4 v[160:163], v136, s[20:21]
	global_load_dwordx4 v[172:175], v136, s[22:23] offset:16
	global_load_dwordx4 v[168:171], v136, s[22:23]
	s_waitcnt lgkmcnt(1)
	s_waitcnt vmcnt(5)
	v_cndmask_b32_e64 v228, v228, -v228, s[56:57]
	v_cndmask_b32_e64 v229, v229, -v229, s[56:57]
	v_cndmask_b32_e64 v230, v230, -v230, s[56:57]
	v_cndmask_b32_e64 v231, v231, -v231, s[56:57]
	v_cndmask_b32_e64 v132, v132, -v132, s[56:57]
	v_cndmask_b32_e64 v133, v133, -v133, s[56:57]
	v_cndmask_b32_e64 v134, v134, -v134, s[56:57]
	v_cndmask_b32_e64 v135, v135, -v135, s[56:57]
	v_mul_f32_e32 v176, v212, v176
	v_mul_f32_e32 v177, v213, v177
	v_mul_f32_e32 v178, v214, v178
	v_mul_f32_e32 v179, v215, v179
	v_mul_f32_e32 v180, v216, v180
	v_mul_f32_e32 v181, v217, v181
	v_mul_f32_e32 v182, v218, v182
	v_mul_f32_e32 v183, v219, v183
	v_mul_f32_e32 v184, v228, v184
	v_mul_f32_e32 v185, v229, v185
	v_mul_f32_e32 v186, v230, v186
	v_mul_f32_e32 v187, v231, v187
	v_mul_f32_e32 v190, v132, v190
	v_mul_f32_e32 v191, v133, v191
	v_mul_f32_e32 v192, v134, v192
	v_mul_f32_e32 v193, v135, v193
	v_add_f32_e32 v176, v176, v184
	v_add_f32_e32 v177, v177, v185
	v_add_f32_e32 v178, v178, v186
	v_add_f32_e32 v179, v179, v187
	v_add_f32_e32 v180, v180, v190
	v_add_f32_e32 v181, v181, v191
	v_add_f32_e32 v182, v182, v192
	v_add_f32_e32 v183, v183, v193
	v_cndmask_b32_e64 v212, v212, v176, s[54:55]
	v_cndmask_b32_e64 v213, v213, v177, s[54:55]
	v_cndmask_b32_e64 v214, v214, v178, s[54:55]
	v_cndmask_b32_e64 v215, v215, v179, s[54:55]
	v_cndmask_b32_e64 v216, v216, v180, s[54:55]
	v_cndmask_b32_e64 v217, v217, v181, s[54:55]
	v_cndmask_b32_e64 v218, v218, v182, s[54:55]
	v_cndmask_b32_e64 v219, v219, v183, s[54:55]
	v_cvt_pk_bf16_f32 v228, v212, v213
	v_cvt_pk_bf16_f32 v229, v214, v215
	v_cvt_pk_bf16_f32 v230, v216, v217
	v_cvt_pk_bf16_f32 v231, v218, v219
	v_lshl_add_u64 v[132:133], s[16:17], 1, v[142:143]
	global_store_dwordx4 v[132:133], v[228:231], off
	s_waitcnt lgkmcnt(0)
	v_mul_f32_e32 v188, s9, v188
	v_mul_f32_e32 v212, v52, v188
	v_mul_f32_e32 v213, v53, v188
	v_mul_f32_e32 v214, v54, v188
	v_mul_f32_e32 v215, v55, v188
	v_mul_f32_e32 v216, v44, v188
	v_mul_f32_e32 v217, v45, v188
	v_mul_f32_e32 v218, v46, v188
	v_mul_f32_e32 v219, v47, v188
	ds_bpermute_b32 v228, v0, v212
	ds_bpermute_b32 v229, v0, v213
	ds_bpermute_b32 v230, v0, v214
	ds_bpermute_b32 v231, v0, v215
	ds_bpermute_b32 v132, v0, v216
	ds_bpermute_b32 v133, v0, v217
	ds_bpermute_b32 v134, v0, v218
	ds_bpermute_b32 v135, v0, v219
	ds_read_b32 v189, v154 offset:704
	v_or_b32_e32 v136, 0x600, v159
	global_load_dwordx4 v[180:183], v136, s[20:21] offset:16
	global_load_dwordx4 v[176:179], v136, s[20:21]
	global_load_dwordx4 v[190:193], v136, s[22:23] offset:16
	global_load_dwordx4 v[184:187], v136, s[22:23]
	s_waitcnt lgkmcnt(1)
	s_waitcnt vmcnt(5)
	v_cndmask_b32_e64 v228, v228, -v228, s[56:57]
	v_cndmask_b32_e64 v229, v229, -v229, s[56:57]
	v_cndmask_b32_e64 v230, v230, -v230, s[56:57]
	v_cndmask_b32_e64 v231, v231, -v231, s[56:57]
	v_cndmask_b32_e64 v132, v132, -v132, s[56:57]
	v_cndmask_b32_e64 v133, v133, -v133, s[56:57]
	v_cndmask_b32_e64 v134, v134, -v134, s[56:57]
	v_cndmask_b32_e64 v135, v135, -v135, s[56:57]
	v_mul_f32_e32 v160, v212, v160
	v_mul_f32_e32 v161, v213, v161
	v_mul_f32_e32 v162, v214, v162
	v_mul_f32_e32 v163, v215, v163
	v_mul_f32_e32 v164, v216, v164
	v_mul_f32_e32 v165, v217, v165
	v_mul_f32_e32 v166, v218, v166
	v_mul_f32_e32 v167, v219, v167
	v_mul_f32_e32 v168, v228, v168
	v_mul_f32_e32 v169, v229, v169
	v_mul_f32_e32 v170, v230, v170
	v_mul_f32_e32 v171, v231, v171
	v_mul_f32_e32 v172, v132, v172
	v_mul_f32_e32 v173, v133, v173
	v_mul_f32_e32 v174, v134, v174
	v_mul_f32_e32 v175, v135, v175
	v_add_f32_e32 v160, v160, v168
	v_add_f32_e32 v161, v161, v169
	v_add_f32_e32 v162, v162, v170
	v_add_f32_e32 v163, v163, v171
	v_add_f32_e32 v164, v164, v172
	v_add_f32_e32 v165, v165, v173
	v_add_f32_e32 v166, v166, v174
	v_add_f32_e32 v167, v167, v175
	v_cndmask_b32_e64 v212, v212, v160, s[54:55]
	v_cndmask_b32_e64 v213, v213, v161, s[54:55]
	v_cndmask_b32_e64 v214, v214, v162, s[54:55]
	v_cndmask_b32_e64 v215, v215, v163, s[54:55]
	v_cndmask_b32_e64 v216, v216, v164, s[54:55]
	v_cndmask_b32_e64 v217, v217, v165, s[54:55]
	v_cndmask_b32_e64 v218, v218, v166, s[54:55]
	v_cndmask_b32_e64 v219, v219, v167, s[54:55]
	v_cvt_pk_bf16_f32 v228, v212, v213
	v_cvt_pk_bf16_f32 v229, v214, v215
	v_cvt_pk_bf16_f32 v230, v216, v217
	v_cvt_pk_bf16_f32 v231, v218, v219
	v_lshl_add_u64 v[132:133], s[14:15], 1, v[142:143]
	global_store_dwordx4 v[132:133], v[228:231], off
	s_waitcnt lgkmcnt(0)
	v_mul_f32_e32 v189, s9, v189
	v_mul_f32_e32 v212, v24, v189
	v_mul_f32_e32 v213, v25, v189
	v_mul_f32_e32 v214, v26, v189
	v_mul_f32_e32 v215, v27, v189
	v_mul_f32_e32 v216, v20, v189
	v_mul_f32_e32 v217, v21, v189
	v_mul_f32_e32 v218, v22, v189
	v_mul_f32_e32 v219, v23, v189
	ds_bpermute_b32 v228, v0, v212
	ds_bpermute_b32 v229, v0, v213
	ds_bpermute_b32 v230, v0, v214
	ds_bpermute_b32 v231, v0, v215
	ds_bpermute_b32 v132, v0, v216
	ds_bpermute_b32 v133, v0, v217
	ds_bpermute_b32 v134, v0, v218
	ds_bpermute_b32 v135, v0, v219
	s_waitcnt lgkmcnt(0)
	s_waitcnt vmcnt(1)
	v_cndmask_b32_e64 v228, v228, -v228, s[56:57]
	v_cndmask_b32_e64 v229, v229, -v229, s[56:57]
	v_cndmask_b32_e64 v230, v230, -v230, s[56:57]
	v_cndmask_b32_e64 v231, v231, -v231, s[56:57]
	v_cndmask_b32_e64 v132, v132, -v132, s[56:57]
	v_cndmask_b32_e64 v133, v133, -v133, s[56:57]
	v_cndmask_b32_e64 v134, v134, -v134, s[56:57]
	v_cndmask_b32_e64 v135, v135, -v135, s[56:57]
	v_mul_f32_e32 v176, v212, v176
	v_mul_f32_e32 v177, v213, v177
	v_mul_f32_e32 v178, v214, v178
	v_mul_f32_e32 v179, v215, v179
	v_mul_f32_e32 v180, v216, v180
	v_mul_f32_e32 v181, v217, v181
	v_mul_f32_e32 v182, v218, v182
	v_mul_f32_e32 v183, v219, v183
	v_mul_f32_e32 v184, v228, v184
	v_mul_f32_e32 v185, v229, v185
	v_mul_f32_e32 v186, v230, v186
	v_mul_f32_e32 v187, v231, v187
	v_mul_f32_e32 v190, v132, v190
	v_mul_f32_e32 v191, v133, v191
	v_mul_f32_e32 v192, v134, v192
	v_mul_f32_e32 v193, v135, v193
	v_add_f32_e32 v176, v176, v184
	v_add_f32_e32 v177, v177, v185
	v_add_f32_e32 v178, v178, v186
	v_add_f32_e32 v179, v179, v187
	v_add_f32_e32 v180, v180, v190
	v_add_f32_e32 v181, v181, v191
	v_add_f32_e32 v182, v182, v192
	v_add_f32_e32 v183, v183, v193
	v_cndmask_b32_e64 v212, v212, v176, s[54:55]
	v_cndmask_b32_e64 v213, v213, v177, s[54:55]
	v_cndmask_b32_e64 v214, v214, v178, s[54:55]
	v_cndmask_b32_e64 v215, v215, v179, s[54:55]
	v_cndmask_b32_e64 v216, v216, v180, s[54:55]
	v_cndmask_b32_e64 v217, v217, v181, s[54:55]
	v_cndmask_b32_e64 v218, v218, v182, s[54:55]
	v_cndmask_b32_e64 v219, v219, v183, s[54:55]
	v_cvt_pk_bf16_f32 v228, v212, v213
	v_cvt_pk_bf16_f32 v229, v214, v215
	v_cvt_pk_bf16_f32 v230, v216, v217
	v_cvt_pk_bf16_f32 v231, v218, v219
	v_lshl_add_u64 v[132:133], s[12:13], 1, v[142:143]
	global_store_dwordx4 v[132:133], v[228:231], off
